# attention V^T staging: 4x4 dword transpose across 16-lane rows (permlane32/16 swap) + v_perm pack, 4 ds_write_b64 instead of 16 ds_write_b16 per thread per tile; same LDS image
# baseline (speedup 1.0000x reference)
; __device__ __forceinline__ void dsa_attn_unit(const Ctx& c, int l, int b, int kvh, int qb64) {
;     ...
;         if (it + 1 < ntile) ATT_STORE(bi ^ 1);
.LBB0_1438:
	s_waitcnt vmcnt(0)
	s_xor_b32 s4, s9, 1
	s_mul_i32 s5, s4, 0x4400
	s_mulk_i32 s4, 0x5000
	v_add_u32_e32 v64, s4, v182
	v_add3_u32 v65, v169, s5, v165
	v_lshl_add_u32 v66, v183, 1, v64
	v_lshl_add_u32 v64, v184, 1, v64
	ds_write_b128 v65, v[112:115]
	ds_write_b128 v65, v[120:123] offset:8704
	v_permlane32_swap_b32_e32 v116, v118
	v_permlane32_swap_b32_e32 v117, v119
	v_permlane32_swap_b32_e32 v124, v126
	v_permlane32_swap_b32_e32 v125, v127
	v_mbcnt_lo_u32_b32 v67, -1, 0
	v_mbcnt_hi_u32_b32 v67, -1, v67
	v_permlane16_swap_b32_e32 v116, v117
	v_permlane16_swap_b32_e32 v118, v119
	v_permlane16_swap_b32_e32 v124, v125
	v_permlane16_swap_b32_e32 v126, v127
	v_bfe_u32 v67, v67, 4, 2
	v_mul_u32_u24_e32 v67, 0x13e, v67
	s_mov_b32 s4, 0x5040100
	s_mov_b32 s5, 0x7060302
	v_perm_b32 v68, v117, v116, s4
	v_perm_b32 v69, v119, v118, s4
	v_perm_b32 v116, v117, v116, s5
	v_perm_b32 v117, v119, v118, s5
	v_perm_b32 v70, v125, v124, s4
	v_perm_b32 v71, v127, v126, s4
	v_perm_b32 v124, v125, v124, s5
	v_perm_b32 v125, v127, v126, s5
	v_add_u32_e32 v66, v66, v67
	v_add_u32_e32 v64, v64, v67
	ds_write_b64 v66, v[68:69]
	ds_write_b64 v66, v[116:117] offset:160
	ds_write_b64 v64, v[70:71]
	ds_write_b64 v64, v[124:125] offset:160

; __device__ __forceinline__ void dsa_attn_unit(const Ctx& c, int l, int b, int kvh, int qb64) {
;     ...
;         if (it + 1 < ntile) ATT_STORE(bi ^ 1);
.LBB0_2888:
	s_waitcnt vmcnt(0)
	s_xor_b32 s6, s11, 1
	s_mul_i32 s7, s6, 0x4400
	s_mulk_i32 s6, 0x5000
	v_add_u32_e32 v64, s6, v182
	v_add3_u32 v65, v169, s7, v165
	v_lshl_add_u32 v66, v183, 1, v64
	v_lshl_add_u32 v64, v184, 1, v64
	ds_write_b128 v65, v[112:115]
	ds_write_b128 v65, v[120:123] offset:8704
	v_permlane32_swap_b32_e32 v116, v118
	v_permlane32_swap_b32_e32 v117, v119
	v_permlane32_swap_b32_e32 v124, v126
	v_permlane32_swap_b32_e32 v125, v127
	v_mbcnt_lo_u32_b32 v67, -1, 0
	v_mbcnt_hi_u32_b32 v67, -1, v67
	v_permlane16_swap_b32_e32 v116, v117
	v_permlane16_swap_b32_e32 v118, v119
	v_permlane16_swap_b32_e32 v124, v125
	v_permlane16_swap_b32_e32 v126, v127
	v_bfe_u32 v67, v67, 4, 2
	v_mul_u32_u24_e32 v67, 0x13e, v67
	s_mov_b32 s6, 0x5040100
	s_mov_b32 s7, 0x7060302
	v_perm_b32 v68, v117, v116, s6
	v_perm_b32 v69, v119, v118, s6
	v_perm_b32 v116, v117, v116, s7
	v_perm_b32 v117, v119, v118, s7
	v_perm_b32 v70, v125, v124, s6
	v_perm_b32 v71, v127, v126, s6
	v_perm_b32 v124, v125, v124, s7
	v_perm_b32 v125, v127, v126, s7
	v_add_u32_e32 v66, v66, v67
	v_add_u32_e32 v64, v64, v67
	ds_write_b64 v66, v[68:69]
	ds_write_b64 v66, v[116:117] offset:160
	ds_write_b64 v64, v[70:71]
	ds_write_b64 v64, v[124:125] offset:160
